# LN epilogue: gain/bias preloaded per tile, no vmcnt(0) per sub-block
# baseline (speedup 1.0000x reference)
;     __device__ __forceinline__ void operator()(f32x4 (&acc)[2][2][4][2], const Unit& u, int wr, int wc, int fr, int fq, LAS unsigned char* lds) const {
;     ...
;             for (int m = 0; m < 4; ++m) { float sv = 0.f, qv = 0.f;
; #pragma unroll
;                 for (int bj = 0; bj < 2; ++bj)
; #pragma unroll
;                     for (int n = 0; n < 2; ++n) { const f32x4 x = acc[ai][bj][m][n]; sv += (x[0] + x[1]) + (x[2] + x[3]); qv += (x[0] * x[0] + x[1] * x[1]) + (x[2] * x[2] + x[3] * x[3]); }
;                 sv += __shfl_xor(sv, 16); sv += __shfl_xor(sv, 32); qv += __shfl_xor(qv, 16); qv += __shfl_xor(qv, 32);
;                 if (fq == 0) P[(ai * HALF + wr * 64 + m * 16 + fr) * 4 + wc] = (f32x2){sv, qv};
;                 __builtin_amdgcn_sched_barrier(0); }
;     ...
;                     for (int n = 0; n < 2; ++n) { const f32x4 gn = *(const f32x4*)(gain + col0 + bj * HALF + n * 16), bs = *(const f32x4*)(bias + col0 + bj * HALF + n * 16);
.LBB0_369:
	global_load_dwordx4 v[204:207], v[138:139], off
	global_load_dwordx4 v[208:211], v[138:139], off offset:64
	global_load_dwordx4 v[212:215], v[138:139], off offset:512
	global_load_dwordx4 v[216:219], v[138:139], off offset:576
	global_load_dwordx4 v[220:223], v[140:141], off
	global_load_dwordx4 v[224:227], v[140:141], off offset:64
	global_load_dwordx4 v[228:231], v[140:141], off offset:512
	global_load_dwordx4 v[232:235], v[140:141], off offset:576
	v_and_b32_e32 v147, 64, v198
	v_xor_b32_e32 v146, 16, v198
	v_add_u32_e32 v176, 64, v147
	v_cmp_lt_i32_e32 vcc, v146, v176
	v_mul_f32_e32 v150, v122, v122
	v_add_f32_e32 v148, v126, v127
	v_cndmask_b32_e32 v146, v198, v146, vcc
	v_lshlrev_b32_e32 v151, 2, v146
	v_add_f32_e32 v146, v124, v125
	v_mul_f32_e32 v173, v124, v124
	v_mul_f32_e32 v175, v125, v125
	v_mul_f32_e32 v179, v126, v126
	v_mul_f32_e32 v181, v127, v127
	v_mul_f32_e32 v147, v120, v120
	v_mul_f32_e32 v149, v121, v121
	v_pk_fma_f32 v[182:183], v[122:123], v[122:123], v[150:151] op_sel_hi:[1,1,0]
	v_mov_b32_e32 v172, v120
	v_mov_b32_e32 v174, v121
	v_mov_b32_e32 v178, v122
	v_mov_b32_e32 v180, v123
	v_pk_add_f32 v[172:173], v[172:173], v[174:175]
	v_pk_add_f32 v[174:175], v[178:179], v[180:181]
	v_pk_add_f32 v[146:147], v[146:147], v[148:149]
	v_mov_b32_e32 v182, v177
	v_mul_f32_e32 v185, v116, v116
	v_mul_f32_e32 v187, v117, v117
	v_mul_f32_e32 v189, v118, v118
	v_mul_f32_e32 v191, v119, v119
	v_pk_add_f32 v[172:173], v[172:173], v[174:175]
	v_pk_add_f32 v[146:147], v[146:147], v[182:183]
	v_mov_b32_e32 v184, v116
	v_mov_b32_e32 v186, v117
	v_mov_b32_e32 v188, v118
	v_mov_b32_e32 v190, v119
	v_pk_add_f32 v[146:147], v[172:173], v[146:147]
	v_pk_add_f32 v[148:149], v[184:185], v[186:187]
	v_pk_add_f32 v[172:173], v[188:189], v[190:191]
	v_mul_f32_e32 v193, v112, v112
	v_mul_f32_e32 v195, v113, v113
	v_mul_f32_e32 v197, v114, v114
	v_mul_f32_e32 v201, v115, v115
	v_pk_add_f32 v[148:149], v[148:149], v[172:173]
	v_mov_b32_e32 v192, v112
	v_mov_b32_e32 v194, v113
	v_mov_b32_e32 v196, v114
	v_mov_b32_e32 v200, v115
	v_pk_add_f32 v[146:147], v[146:147], v[148:149]
	v_pk_add_f32 v[148:149], v[192:193], v[194:195]
	v_pk_add_f32 v[172:173], v[196:197], v[200:201]
	v_xor_b32_e32 v150, 32, v198
	v_pk_add_f32 v[148:149], v[148:149], v[172:173]
	v_cmp_lt_i32_e32 vcc, v150, v176
	v_pk_add_f32 v[146:147], v[146:147], v[148:149]
	ds_bpermute_b32 v148, v151, v146
	ds_bpermute_b32 v149, v151, v147
	v_cndmask_b32_e32 v150, v198, v150, vcc
	v_lshlrev_b32_e32 v172, 2, v150
	v_mov_b32_e32 v150, v252
	s_waitcnt lgkmcnt(0)
	v_pk_add_f32 v[146:147], v[146:147], v[148:149]
	ds_bpermute_b32 v148, v172, v146
	ds_bpermute_b32 v149, v172, v147
	v_readfirstlane_b32 s22, v150
	s_and_saveexec_b64 s[40:41], s[36:37]
	s_cbranch_execz .LBB0_371
	s_waitcnt lgkmcnt(0)
	v_pk_add_f32 v[146:147], v[146:147], v[148:149]
	ds_write_b64 v171, v[146:147]

; __device__ __forceinline__ unsigned cvt_pk_bf16(float lo, float hi) { unsigned r; asm volatile("v_cvt_pk_bf16_f32 %0, %1, %2" : "=v"(r) : "v"(lo), "v"(hi)); return r; }
;     __device__ __forceinline__ void operator()(f32x4 (&acc)[2][2][4][2], const Unit& u, int wr, int wc, int fr, int fq, LAS unsigned char* lds) const {
;     ...
; #pragma unroll
;         for (int ai = 0; ai < 2; ++ai)
; #pragma unroll
;             for (int m = 0; m < 4; ++m) { const int r = ai * HALF + wr * 64 + m * 16 + fr; const f32x2 sr = ST[r]; const size_t off = (size_t)(u.pm * BM + r) * DM + col0;
; #pragma unroll
;                 for (int bj = 0; bj < 2; ++bj)
; #pragma unroll
;                     for (int n = 0; n < 2; ++n) { const f32x4 gn = *(const f32x4*)(gain + col0 + bj * HALF + n * 16), bs = *(const f32x4*)(bias + col0 + bj * HALF + n * 16);
;                         const f32x4 o = (acc[ai][bj][m][n] - sr.x) * sr.y * gn + bs; *(f32x4*)(out + off + bj * HALF + n * 16) = o;
;                         if (write_xb) { u32x2 w; w.x = cvt_pk_bf16(o[0], o[1]); w.y = cvt_pk_bf16(o[2], o[3]); *(u32x2*)(xb + off + bj * HALF + n * 16) = w; }
;                         __builtin_amdgcn_sched_barrier(0); }
;                 asm volatile("" ::: "memory"); }
.LBB0_399:
	s_or_b64 exec, exec, s[78:79]
	s_waitcnt lgkmcnt(0)
	v_add_u32_e32 v148, s21, v152
	s_waitcnt lgkmcnt(0)
	s_barrier
	v_ashrrev_i32_e32 v149, 31, v148
	ds_read_b64 v[146:147], v162
	v_lshlrev_b64 v[178:179], 11, v[148:149]
	v_or_b32_e32 v178, v178, v153
	s_andn2_b64 vcc, exec, s[42:43]
	s_waitcnt lgkmcnt(0)
	v_sub_f32_e32 v127, v127, v146
	v_sub_f32_e32 v126, v126, v146
	v_sub_f32_e32 v125, v125, v146
	v_sub_f32_e32 v124, v124, v146
	v_pk_mul_f32 v[126:127], v[146:147], v[126:127] op_sel:[1,0]
	v_pk_mul_f32 v[124:125], v[146:147], v[124:125] op_sel:[1,0]
	v_pk_fma_f32 v[126:127], v[206:207], v[126:127], v[222:223]
	v_cndmask_b32_e64 v150, 0, 1, s[42:43]
	v_pk_fma_f32 v[124:125], v[204:205], v[124:125], v[220:221]
	v_lshl_add_u64 v[148:149], v[178:179], 2, s[96:97]
	v_cmp_ne_u32_e64 s[40:41], 1, v150
	v_lshl_add_u64 v[150:151], v[178:179], 1, s[6:7]
	global_store_dwordx4 v[148:149], v[124:127], off
	s_cbranch_vccnz .LBB0_401
	s_nop 0
	v_cvt_pk_bf16_f32 v124, v124, v125
	v_cvt_pk_bf16_f32 v125, v126, v127
	global_store_dwordx2 v[150:151], v[124:125], off
.LBB0_401:
	s_nop 0
	v_mov_b32_e32 v124, v147
	v_mov_b32_e32 v125, v147
	v_sub_f32_e32 v123, v123, v146
	v_sub_f32_e32 v122, v122, v146
	v_sub_f32_e32 v121, v121, v146
	v_sub_f32_e32 v120, v120, v146
	v_mov_b32_e32 v126, v147
	v_mov_b32_e32 v127, v147
	v_pk_mul_f32 v[120:121], v[124:125], v[120:121]
	v_pk_mul_f32 v[122:123], v[126:127], v[122:123]
	s_and_b64 vcc, exec, s[40:41]
	v_pk_fma_f32 v[122:123], v[122:123], v[210:211], v[226:227]
	v_pk_fma_f32 v[120:121], v[120:121], v[208:209], v[224:225]
	global_store_dwordx4 v[148:149], v[120:123], off offset:64
	s_cbranch_vccnz .LBB0_403
	s_nop 0
	v_cvt_pk_bf16_f32 v120, v120, v121
	v_cvt_pk_bf16_f32 v121, v122, v123
	global_store_dwordx2 v[150:151], v[120:121], off offset:32
.LBB0_403:
	s_nop 0
	v_sub_f32_e32 v119, v119, v146
	v_sub_f32_e32 v118, v118, v146
	v_sub_f32_e32 v117, v117, v146
	v_sub_f32_e32 v116, v116, v146
	v_pk_mul_f32 v[116:117], v[124:125], v[116:117]
	v_pk_mul_f32 v[118:119], v[126:127], v[118:119]
	s_and_b64 vcc, exec, s[40:41]
	v_pk_fma_f32 v[118:119], v[118:119], v[214:215], v[230:231]
	v_pk_fma_f32 v[116:117], v[116:117], v[212:213], v[228:229]
	global_store_dwordx4 v[148:149], v[116:119], off offset:512
	s_cbranch_vccnz .LBB0_405
	s_nop 0
	v_cvt_pk_bf16_f32 v116, v116, v117
	v_cvt_pk_bf16_f32 v117, v118, v119
	global_store_dwordx2 v[150:151], v[116:117], off offset:256
.LBB0_405:
	s_nop 0
	v_sub_f32_e32 v115, v115, v146
	v_sub_f32_e32 v114, v114, v146
	v_sub_f32_e32 v113, v113, v146
	v_sub_f32_e32 v112, v112, v146
	v_mov_b32_e32 v146, v147
	v_pk_mul_f32 v[112:113], v[124:125], v[112:113]
	v_pk_mul_f32 v[114:115], v[146:147], v[114:115]
	s_and_b64 vcc, exec, s[40:41]
	v_pk_fma_f32 v[114:115], v[114:115], v[218:219], v[234:235]
	v_pk_fma_f32 v[112:113], v[112:113], v[216:217], v[232:233]
	global_store_dwordx4 v[148:149], v[112:115], off offset:576
	s_cbranch_vccnz .LBB0_407
	s_nop 0
	v_cvt_pk_bf16_f32 v112, v112, v113
	v_cvt_pk_bf16_f32 v113, v114, v115
	global_store_dwordx2 v[150:151], v[112:113], off offset:288
.LBB0_407:
	s_nop 0
	v_add_u32_e32 v114, s21, v154
	v_ashrrev_i32_e32 v115, 31, v114
	ds_read_b64 v[112:113], v163
	v_lshlrev_b64 v[122:123], 11, v[114:115]
	v_or_b32_e32 v122, v122, v153
	s_and_b64 vcc, exec, s[40:41]
	s_waitcnt lgkmcnt(0)
	v_sub_f32_e32 v111, v111, v112
	v_sub_f32_e32 v110, v110, v112
	v_sub_f32_e32 v109, v109, v112
	v_sub_f32_e32 v108, v108, v112
	v_pk_mul_f32 v[108:109], v[112:113], v[108:109] op_sel:[1,0]
	v_pk_mul_f32 v[110:111], v[112:113], v[110:111] op_sel:[1,0]
	v_pk_fma_f32 v[108:109], v[204:205], v[108:109], v[220:221]
	v_pk_fma_f32 v[110:111], v[206:207], v[110:111], v[222:223]
	v_lshl_add_u64 v[114:115], v[122:123], 2, s[96:97]
	v_lshl_add_u64 v[116:117], v[122:123], 1, s[6:7]
	global_store_dwordx4 v[114:115], v[108:111], off
	s_cbranch_vccnz .LBB0_409
	s_nop 0
	v_cvt_pk_bf16_f32 v108, v108, v109
	v_cvt_pk_bf16_f32 v109, v110, v111
	global_store_dwordx2 v[116:117], v[108:109], off
.LBB0_409:
	s_nop 0
	v_mov_b32_e32 v108, v113
	v_mov_b32_e32 v109, v113
	v_sub_f32_e32 v107, v107, v112
	v_sub_f32_e32 v106, v106, v112
	v_sub_f32_e32 v105, v105, v112
	v_sub_f32_e32 v104, v104, v112
	v_mov_b32_e32 v110, v113
	v_mov_b32_e32 v111, v113
	v_pk_mul_f32 v[104:105], v[108:109], v[104:105]
	v_pk_mul_f32 v[106:107], v[110:111], v[106:107]
	s_and_b64 vcc, exec, s[40:41]
	v_pk_fma_f32 v[106:107], v[106:107], v[210:211], v[226:227]
	v_pk_fma_f32 v[104:105], v[104:105], v[208:209], v[224:225]
	global_store_dwordx4 v[114:115], v[104:107], off offset:64
	s_cbranch_vccnz .LBB0_411
	s_nop 0
	v_cvt_pk_bf16_f32 v104, v104, v105
	v_cvt_pk_bf16_f32 v105, v106, v107
	global_store_dwordx2 v[116:117], v[104:105], off offset:32
.LBB0_411:
	s_nop 0
	v_sub_f32_e32 v103, v103, v112
	v_sub_f32_e32 v102, v102, v112
	v_sub_f32_e32 v101, v101, v112
	v_sub_f32_e32 v100, v100, v112
	v_pk_mul_f32 v[100:101], v[108:109], v[100:101]
	v_pk_mul_f32 v[102:103], v[110:111], v[102:103]
	s_and_b64 vcc, exec, s[40:41]
	v_pk_fma_f32 v[102:103], v[102:103], v[214:215], v[230:231]
	v_pk_fma_f32 v[100:101], v[100:101], v[212:213], v[228:229]
	global_store_dwordx4 v[114:115], v[100:103], off offset:512
	s_cbranch_vccnz .LBB0_413
	s_nop 0
	v_cvt_pk_bf16_f32 v100, v100, v101
	v_cvt_pk_bf16_f32 v101, v102, v103
	global_store_dwordx2 v[116:117], v[100:101], off offset:256
; __device__ __forceinline__ unsigned cvt_pk_bf16(float lo, float hi) { unsigned r; asm volatile("v_cvt_pk_bf16_f32 %0, %1, %2" : "=v"(r) : "v"(lo), "v"(hi)); return r; }
;     __device__ __forceinline__ void operator()(f32x4 (&acc)[2][2][4][2], const Unit& u, int wr, int wc, int fr, int fq, LAS unsigned char* lds) const {
;     ...
; #pragma unroll
;         for (int ai = 0; ai < 2; ++ai)
; #pragma unroll
;             for (int m = 0; m < 4; ++m) { const int r = ai * HALF + wr * 64 + m * 16 + fr; const f32x2 sr = ST[r]; const size_t off = (size_t)(u.pm * BM + r) * DM + col0;
; #pragma unroll
;                 for (int bj = 0; bj < 2; ++bj)
; #pragma unroll
;                     for (int n = 0; n < 2; ++n) { const f32x4 gn = *(const f32x4*)(gain + col0 + bj * HALF + n * 16), bs = *(const f32x4*)(bias + col0 + bj * HALF + n * 16);
;                         const f32x4 o = (acc[ai][bj][m][n] - sr.x) * sr.y * gn + bs; *(f32x4*)(out + off + bj * HALF + n * 16) = o;
;                         if (write_xb) { u32x2 w; w.x = cvt_pk_bf16(o[0], o[1]); w.y = cvt_pk_bf16(o[2], o[3]); *(u32x2*)(xb + off + bj * HALF + n * 16) = w; }
;                         __builtin_amdgcn_sched_barrier(0); }
;                 asm volatile("" ::: "memory"); }
.LBB0_413:
	s_nop 0
	v_sub_f32_e32 v99, v99, v112
	v_sub_f32_e32 v98, v98, v112
	v_sub_f32_e32 v97, v97, v112
	v_sub_f32_e32 v96, v96, v112
	v_mov_b32_e32 v112, v113
	v_pk_mul_f32 v[96:97], v[108:109], v[96:97]
	v_pk_mul_f32 v[98:99], v[112:113], v[98:99]
	s_and_b64 vcc, exec, s[40:41]
	v_pk_fma_f32 v[98:99], v[98:99], v[218:219], v[234:235]
	v_pk_fma_f32 v[96:97], v[96:97], v[216:217], v[232:233]
	global_store_dwordx4 v[114:115], v[96:99], off offset:576
	s_cbranch_vccnz .LBB0_415
	s_nop 0
	v_cvt_pk_bf16_f32 v96, v96, v97
	v_cvt_pk_bf16_f32 v97, v98, v99
	global_store_dwordx2 v[116:117], v[96:97], off offset:288
.LBB0_415:
	s_nop 0
	v_add_u32_e32 v98, s21, v155
	v_ashrrev_i32_e32 v99, 31, v98
	ds_read_b64 v[96:97], v164
	v_lshlrev_b64 v[106:107], 11, v[98:99]
	v_or_b32_e32 v106, v106, v153
	s_and_b64 vcc, exec, s[40:41]
	s_waitcnt lgkmcnt(0)
	v_sub_f32_e32 v95, v95, v96
	v_sub_f32_e32 v94, v94, v96
	v_sub_f32_e32 v93, v93, v96
	v_sub_f32_e32 v92, v92, v96
	v_pk_mul_f32 v[92:93], v[96:97], v[92:93] op_sel:[1,0]
	v_pk_mul_f32 v[94:95], v[96:97], v[94:95] op_sel:[1,0]
	v_pk_fma_f32 v[92:93], v[204:205], v[92:93], v[220:221]
	v_pk_fma_f32 v[94:95], v[206:207], v[94:95], v[222:223]
	v_lshl_add_u64 v[98:99], v[106:107], 2, s[96:97]
	v_lshl_add_u64 v[100:101], v[106:107], 1, s[6:7]
	global_store_dwordx4 v[98:99], v[92:95], off
	s_cbranch_vccnz .LBB0_417
	s_nop 0
	v_cvt_pk_bf16_f32 v92, v92, v93
	v_cvt_pk_bf16_f32 v93, v94, v95
	global_store_dwordx2 v[100:101], v[92:93], off
.LBB0_417:
	s_nop 0
	v_mov_b32_e32 v92, v97
	v_mov_b32_e32 v93, v97
	v_sub_f32_e32 v91, v91, v96
	v_sub_f32_e32 v90, v90, v96
	v_sub_f32_e32 v89, v89, v96
	v_sub_f32_e32 v88, v88, v96
	v_mov_b32_e32 v94, v97
	v_mov_b32_e32 v95, v97
	v_pk_mul_f32 v[88:89], v[92:93], v[88:89]
	v_pk_mul_f32 v[90:91], v[94:95], v[90:91]
	s_and_b64 vcc, exec, s[40:41]
	v_pk_fma_f32 v[90:91], v[90:91], v[210:211], v[226:227]
	v_pk_fma_f32 v[88:89], v[88:89], v[208:209], v[224:225]
	global_store_dwordx4 v[98:99], v[88:91], off offset:64
	s_cbranch_vccnz .LBB0_419
	s_nop 0
	v_cvt_pk_bf16_f32 v88, v88, v89
	v_cvt_pk_bf16_f32 v89, v90, v91
	global_store_dwordx2 v[100:101], v[88:89], off offset:32
.LBB0_419:
	s_nop 0
	v_sub_f32_e32 v87, v87, v96
	v_sub_f32_e32 v86, v86, v96
	v_sub_f32_e32 v85, v85, v96
	v_sub_f32_e32 v84, v84, v96
	v_pk_mul_f32 v[84:85], v[92:93], v[84:85]
	v_pk_mul_f32 v[86:87], v[94:95], v[86:87]
	s_and_b64 vcc, exec, s[40:41]
	v_pk_fma_f32 v[86:87], v[86:87], v[214:215], v[230:231]
	v_pk_fma_f32 v[84:85], v[84:85], v[212:213], v[228:229]
	global_store_dwordx4 v[98:99], v[84:87], off offset:512
	s_cbranch_vccnz .LBB0_421
	s_nop 0
	v_cvt_pk_bf16_f32 v84, v84, v85
	v_cvt_pk_bf16_f32 v85, v86, v87
	global_store_dwordx2 v[100:101], v[84:85], off offset:256
.LBB0_421:
	s_nop 0
	v_sub_f32_e32 v83, v83, v96
	v_sub_f32_e32 v82, v82, v96
	v_sub_f32_e32 v81, v81, v96
	v_sub_f32_e32 v80, v80, v96
	v_mov_b32_e32 v96, v97
	v_pk_mul_f32 v[80:81], v[92:93], v[80:81]
	v_pk_mul_f32 v[82:83], v[96:97], v[82:83]
	s_and_b64 vcc, exec, s[40:41]
	v_pk_fma_f32 v[82:83], v[82:83], v[218:219], v[234:235]
	v_pk_fma_f32 v[80:81], v[80:81], v[216:217], v[232:233]
	global_store_dwordx4 v[98:99], v[80:83], off offset:576
	s_cbranch_vccnz .LBB0_423
	s_nop 0
	v_cvt_pk_bf16_f32 v80, v80, v81
	v_cvt_pk_bf16_f32 v81, v82, v83
	global_store_dwordx2 v[100:101], v[80:81], off offset:288
.LBB0_423:
	s_nop 0
	v_add_u32_e32 v82, s21, v156
	v_ashrrev_i32_e32 v83, 31, v82
	ds_read_b64 v[80:81], v165
	v_lshlrev_b64 v[90:91], 11, v[82:83]
	v_or_b32_e32 v90, v90, v153
	s_and_b64 vcc, exec, s[40:41]
	s_waitcnt lgkmcnt(0)
	v_sub_f32_e32 v79, v79, v80
	v_sub_f32_e32 v78, v78, v80
	v_sub_f32_e32 v77, v77, v80
	v_sub_f32_e32 v76, v76, v80
	v_pk_mul_f32 v[76:77], v[80:81], v[76:77] op_sel:[1,0]
	v_pk_mul_f32 v[78:79], v[80:81], v[78:79] op_sel:[1,0]
	v_pk_fma_f32 v[76:77], v[204:205], v[76:77], v[220:221]
	v_pk_fma_f32 v[78:79], v[206:207], v[78:79], v[222:223]
	v_lshl_add_u64 v[82:83], v[90:91], 2, s[96:97]
	v_lshl_add_u64 v[84:85], v[90:91], 1, s[6:7]
	global_store_dwordx4 v[82:83], v[76:79], off
	s_cbranch_vccnz .LBB0_425
	s_nop 0
	v_cvt_pk_bf16_f32 v76, v76, v77
	v_cvt_pk_bf16_f32 v77, v78, v79
	global_store_dwordx2 v[84:85], v[76:77], off
.LBB0_425:
	s_nop 0
	v_mov_b32_e32 v76, v81
	v_mov_b32_e32 v77, v81
	v_sub_f32_e32 v75, v75, v80
	v_sub_f32_e32 v74, v74, v80
	v_sub_f32_e32 v73, v73, v80
	v_sub_f32_e32 v72, v72, v80
	v_mov_b32_e32 v78, v81
	v_mov_b32_e32 v79, v81
	v_pk_mul_f32 v[72:73], v[76:77], v[72:73]
	v_pk_mul_f32 v[74:75], v[78:79], v[74:75]
	s_and_b64 vcc, exec, s[40:41]
	v_pk_fma_f32 v[74:75], v[74:75], v[210:211], v[226:227]
	v_pk_fma_f32 v[72:73], v[72:73], v[208:209], v[224:225]
	global_store_dwordx4 v[82:83], v[72:75], off offset:64
	s_cbranch_vccnz .LBB0_427
	s_nop 0
	v_cvt_pk_bf16_f32 v72, v72, v73
	v_cvt_pk_bf16_f32 v73, v74, v75
	global_store_dwordx2 v[84:85], v[72:73], off offset:32
.LBB0_427:
	s_nop 0
	v_sub_f32_e32 v71, v71, v80
	v_sub_f32_e32 v70, v70, v80
	v_sub_f32_e32 v69, v69, v80
	v_sub_f32_e32 v68, v68, v80
	v_pk_mul_f32 v[68:69], v[76:77], v[68:69]
	v_pk_mul_f32 v[70:71], v[78:79], v[70:71]
	s_and_b64 vcc, exec, s[40:41]
	v_pk_fma_f32 v[70:71], v[70:71], v[214:215], v[230:231]
	v_pk_fma_f32 v[68:69], v[68:69], v[212:213], v[228:229]
	global_store_dwordx4 v[82:83], v[68:71], off offset:512
	s_cbranch_vccnz .LBB0_429
	s_nop 0
	v_cvt_pk_bf16_f32 v68, v68, v69
	v_cvt_pk_bf16_f32 v69, v70, v71
	global_store_dwordx2 v[84:85], v[68:69], off offset:256
; __device__ __forceinline__ unsigned cvt_pk_bf16(float lo, float hi) { unsigned r; asm volatile("v_cvt_pk_bf16_f32 %0, %1, %2" : "=v"(r) : "v"(lo), "v"(hi)); return r; }
;     __device__ __forceinline__ void operator()(f32x4 (&acc)[2][2][4][2], const Unit& u, int wr, int wc, int fr, int fq, LAS unsigned char* lds) const {
;     ...
; #pragma unroll
;         for (int ai = 0; ai < 2; ++ai)
; #pragma unroll
;             for (int m = 0; m < 4; ++m) { const int r = ai * HALF + wr * 64 + m * 16 + fr; const f32x2 sr = ST[r]; const size_t off = (size_t)(u.pm * BM + r) * DM + col0;
; #pragma unroll
;                 for (int bj = 0; bj < 2; ++bj)
; #pragma unroll
;                     for (int n = 0; n < 2; ++n) { const f32x4 gn = *(const f32x4*)(gain + col0 + bj * HALF + n * 16), bs = *(const f32x4*)(bias + col0 + bj * HALF + n * 16);
;                         const f32x4 o = (acc[ai][bj][m][n] - sr.x) * sr.y * gn + bs; *(f32x4*)(out + off + bj * HALF + n * 16) = o;
;                         if (write_xb) { u32x2 w; w.x = cvt_pk_bf16(o[0], o[1]); w.y = cvt_pk_bf16(o[2], o[3]); *(u32x2*)(xb + off + bj * HALF + n * 16) = w; }
;                         __builtin_amdgcn_sched_barrier(0); }
;                 asm volatile("" ::: "memory"); }
.LBB0_429:
	s_nop 0
	v_sub_f32_e32 v67, v67, v80
	v_sub_f32_e32 v66, v66, v80
	v_sub_f32_e32 v65, v65, v80
	v_sub_f32_e32 v64, v64, v80
	v_mov_b32_e32 v80, v81
	v_pk_mul_f32 v[64:65], v[76:77], v[64:65]
	v_pk_mul_f32 v[66:67], v[80:81], v[66:67]
	s_and_b64 vcc, exec, s[40:41]
	v_pk_fma_f32 v[66:67], v[66:67], v[218:219], v[234:235]
	v_pk_fma_f32 v[64:65], v[64:65], v[216:217], v[232:233]
	global_store_dwordx4 v[82:83], v[64:67], off offset:576
	s_cbranch_vccnz .LBB0_431
	s_nop 0
	v_cvt_pk_bf16_f32 v64, v64, v65
	v_cvt_pk_bf16_f32 v65, v66, v67
	global_store_dwordx2 v[84:85], v[64:65], off offset:288
.LBB0_431:
	s_nop 0
	v_add_u32_e32 v66, s21, v157
	v_ashrrev_i32_e32 v67, 31, v66
	ds_read_b64 v[64:65], v166
	v_lshlrev_b64 v[74:75], 11, v[66:67]
	v_or_b32_e32 v74, v74, v153
	s_and_b64 vcc, exec, s[40:41]
	s_waitcnt lgkmcnt(0)
	v_sub_f32_e32 v63, v63, v64
	v_sub_f32_e32 v62, v62, v64
	v_sub_f32_e32 v61, v61, v64
	v_sub_f32_e32 v60, v60, v64
	v_pk_mul_f32 v[60:61], v[64:65], v[60:61] op_sel:[1,0]
	v_pk_mul_f32 v[62:63], v[64:65], v[62:63] op_sel:[1,0]
	v_pk_fma_f32 v[60:61], v[204:205], v[60:61], v[220:221]
	v_pk_fma_f32 v[62:63], v[206:207], v[62:63], v[222:223]
	v_lshl_add_u64 v[66:67], v[74:75], 2, s[96:97]
	v_lshl_add_u64 v[68:69], v[74:75], 1, s[6:7]
	global_store_dwordx4 v[66:67], v[60:63], off
	s_cbranch_vccnz .LBB0_433
	s_nop 0
	v_cvt_pk_bf16_f32 v60, v60, v61
	v_cvt_pk_bf16_f32 v61, v62, v63
	global_store_dwordx2 v[68:69], v[60:61], off
.LBB0_433:
	s_nop 0
	v_mov_b32_e32 v60, v65
	v_mov_b32_e32 v61, v65
	v_sub_f32_e32 v59, v59, v64
	v_sub_f32_e32 v58, v58, v64
	v_sub_f32_e32 v57, v57, v64
	v_sub_f32_e32 v56, v56, v64
	v_mov_b32_e32 v62, v65
	v_mov_b32_e32 v63, v65
	v_pk_mul_f32 v[56:57], v[60:61], v[56:57]
	v_pk_mul_f32 v[58:59], v[62:63], v[58:59]
	s_and_b64 vcc, exec, s[40:41]
	v_pk_fma_f32 v[58:59], v[58:59], v[210:211], v[226:227]
	v_pk_fma_f32 v[56:57], v[56:57], v[208:209], v[224:225]
	global_store_dwordx4 v[66:67], v[56:59], off offset:64
	s_cbranch_vccnz .LBB0_435
	s_nop 0
	v_cvt_pk_bf16_f32 v56, v56, v57
	v_cvt_pk_bf16_f32 v57, v58, v59
	global_store_dwordx2 v[68:69], v[56:57], off offset:32
.LBB0_435:
	s_nop 0
	v_sub_f32_e32 v55, v55, v64
	v_sub_f32_e32 v54, v54, v64
	v_sub_f32_e32 v53, v53, v64
	v_sub_f32_e32 v52, v52, v64
	v_pk_mul_f32 v[52:53], v[60:61], v[52:53]
	v_pk_mul_f32 v[54:55], v[62:63], v[54:55]
	s_and_b64 vcc, exec, s[40:41]
	v_pk_fma_f32 v[54:55], v[54:55], v[214:215], v[230:231]
	v_pk_fma_f32 v[52:53], v[52:53], v[212:213], v[228:229]
	global_store_dwordx4 v[66:67], v[52:55], off offset:512
	s_cbranch_vccnz .LBB0_437
	s_nop 0
	v_cvt_pk_bf16_f32 v52, v52, v53
	v_cvt_pk_bf16_f32 v53, v54, v55
	global_store_dwordx2 v[68:69], v[52:53], off offset:256
.LBB0_437:
	s_nop 0
	v_sub_f32_e32 v51, v51, v64
	v_sub_f32_e32 v50, v50, v64
	v_sub_f32_e32 v49, v49, v64
	v_sub_f32_e32 v48, v48, v64
	v_mov_b32_e32 v64, v65
	v_pk_mul_f32 v[48:49], v[60:61], v[48:49]
	v_pk_mul_f32 v[50:51], v[64:65], v[50:51]
	s_and_b64 vcc, exec, s[40:41]
	v_pk_fma_f32 v[50:51], v[50:51], v[218:219], v[234:235]
	v_pk_fma_f32 v[48:49], v[48:49], v[216:217], v[232:233]
	global_store_dwordx4 v[66:67], v[48:51], off offset:576
	s_cbranch_vccnz .LBB0_439
	s_nop 0
	v_cvt_pk_bf16_f32 v48, v48, v49
	v_cvt_pk_bf16_f32 v49, v50, v51
	global_store_dwordx2 v[68:69], v[48:49], off offset:288
.LBB0_439:
	s_nop 0
	v_add_u32_e32 v50, s21, v158
	v_ashrrev_i32_e32 v51, 31, v50
	ds_read_b64 v[48:49], v167
	v_lshlrev_b64 v[58:59], 11, v[50:51]
	v_or_b32_e32 v58, v58, v153
	s_and_b64 vcc, exec, s[40:41]
	s_waitcnt lgkmcnt(0)
	v_sub_f32_e32 v47, v47, v48
	v_sub_f32_e32 v46, v46, v48
	v_sub_f32_e32 v45, v45, v48
	v_sub_f32_e32 v44, v44, v48
	v_pk_mul_f32 v[44:45], v[48:49], v[44:45] op_sel:[1,0]
	v_pk_mul_f32 v[46:47], v[48:49], v[46:47] op_sel:[1,0]
	v_pk_fma_f32 v[44:45], v[204:205], v[44:45], v[220:221]
	v_pk_fma_f32 v[46:47], v[206:207], v[46:47], v[222:223]
	v_lshl_add_u64 v[50:51], v[58:59], 2, s[96:97]
	v_lshl_add_u64 v[52:53], v[58:59], 1, s[6:7]
	global_store_dwordx4 v[50:51], v[44:47], off
	s_cbranch_vccnz .LBB0_441
	s_nop 0
	v_cvt_pk_bf16_f32 v44, v44, v45
	v_cvt_pk_bf16_f32 v45, v46, v47
	global_store_dwordx2 v[52:53], v[44:45], off
.LBB0_441:
	s_nop 0
	v_mov_b32_e32 v44, v49
	v_mov_b32_e32 v45, v49
	v_sub_f32_e32 v43, v43, v48
	v_sub_f32_e32 v42, v42, v48
	v_sub_f32_e32 v41, v41, v48
	v_sub_f32_e32 v40, v40, v48
	v_mov_b32_e32 v46, v49
	v_mov_b32_e32 v47, v49
	v_pk_mul_f32 v[40:41], v[44:45], v[40:41]
	v_pk_mul_f32 v[42:43], v[46:47], v[42:43]
	s_and_b64 vcc, exec, s[40:41]
	v_pk_fma_f32 v[42:43], v[42:43], v[210:211], v[226:227]
	v_pk_fma_f32 v[40:41], v[40:41], v[208:209], v[224:225]
	global_store_dwordx4 v[50:51], v[40:43], off offset:64
	s_cbranch_vccnz .LBB0_443
	s_nop 0
	v_cvt_pk_bf16_f32 v40, v40, v41
	v_cvt_pk_bf16_f32 v41, v42, v43
	global_store_dwordx2 v[52:53], v[40:41], off offset:32
.LBB0_443:
	s_nop 0
	v_sub_f32_e32 v39, v39, v48
	v_sub_f32_e32 v38, v38, v48
	v_sub_f32_e32 v37, v37, v48
	v_sub_f32_e32 v36, v36, v48
	v_pk_mul_f32 v[36:37], v[44:45], v[36:37]
	v_pk_mul_f32 v[38:39], v[46:47], v[38:39]
	s_and_b64 vcc, exec, s[40:41]
	v_pk_fma_f32 v[38:39], v[38:39], v[214:215], v[230:231]
	v_pk_fma_f32 v[36:37], v[36:37], v[212:213], v[228:229]
	global_store_dwordx4 v[50:51], v[36:39], off offset:512
	s_cbranch_vccnz .LBB0_445
	s_nop 0
	v_cvt_pk_bf16_f32 v36, v36, v37
	v_cvt_pk_bf16_f32 v37, v38, v39
	global_store_dwordx2 v[52:53], v[36:37], off offset:256
; __device__ __forceinline__ unsigned cvt_pk_bf16(float lo, float hi) { unsigned r; asm volatile("v_cvt_pk_bf16_f32 %0, %1, %2" : "=v"(r) : "v"(lo), "v"(hi)); return r; }
;     __device__ __forceinline__ void operator()(f32x4 (&acc)[2][2][4][2], const Unit& u, int wr, int wc, int fr, int fq, LAS unsigned char* lds) const {
;     ...
; #pragma unroll
;         for (int ai = 0; ai < 2; ++ai)
; #pragma unroll
;             for (int m = 0; m < 4; ++m) { const int r = ai * HALF + wr * 64 + m * 16 + fr; const f32x2 sr = ST[r]; const size_t off = (size_t)(u.pm * BM + r) * DM + col0;
; #pragma unroll
;                 for (int bj = 0; bj < 2; ++bj)
; #pragma unroll
;                     for (int n = 0; n < 2; ++n) { const f32x4 gn = *(const f32x4*)(gain + col0 + bj * HALF + n * 16), bs = *(const f32x4*)(bias + col0 + bj * HALF + n * 16);
;                         const f32x4 o = (acc[ai][bj][m][n] - sr.x) * sr.y * gn + bs; *(f32x4*)(out + off + bj * HALF + n * 16) = o;
;                         if (write_xb) { u32x2 w; w.x = cvt_pk_bf16(o[0], o[1]); w.y = cvt_pk_bf16(o[2], o[3]); *(u32x2*)(xb + off + bj * HALF + n * 16) = w; }
;                         __builtin_amdgcn_sched_barrier(0); }
;                 asm volatile("" ::: "memory"); }
.LBB0_445:
	s_nop 0
	v_sub_f32_e32 v35, v35, v48
	v_sub_f32_e32 v34, v34, v48
	v_sub_f32_e32 v33, v33, v48
	v_sub_f32_e32 v32, v32, v48
	v_mov_b32_e32 v48, v49
	v_pk_mul_f32 v[32:33], v[44:45], v[32:33]
	v_pk_mul_f32 v[34:35], v[48:49], v[34:35]
	s_and_b64 vcc, exec, s[40:41]
	v_pk_fma_f32 v[34:35], v[34:35], v[218:219], v[234:235]
	v_pk_fma_f32 v[32:33], v[32:33], v[216:217], v[232:233]
	global_store_dwordx4 v[50:51], v[32:35], off offset:576
	s_cbranch_vccnz .LBB0_447
	s_nop 0
	v_cvt_pk_bf16_f32 v32, v32, v33
	v_cvt_pk_bf16_f32 v33, v34, v35
	global_store_dwordx2 v[52:53], v[32:33], off offset:288
.LBB0_447:
	s_nop 0
	v_add_u32_e32 v34, s21, v159
	v_ashrrev_i32_e32 v35, 31, v34
	ds_read_b64 v[32:33], v168
	v_lshlrev_b64 v[42:43], 11, v[34:35]
	v_or_b32_e32 v42, v42, v153
	s_and_b64 vcc, exec, s[40:41]
	s_waitcnt lgkmcnt(0)
	v_sub_f32_e32 v31, v31, v32
	v_sub_f32_e32 v30, v30, v32
	v_sub_f32_e32 v29, v29, v32
	v_sub_f32_e32 v28, v28, v32
	v_pk_mul_f32 v[28:29], v[32:33], v[28:29] op_sel:[1,0]
	v_pk_mul_f32 v[30:31], v[32:33], v[30:31] op_sel:[1,0]
	v_pk_fma_f32 v[28:29], v[204:205], v[28:29], v[220:221]
	v_pk_fma_f32 v[30:31], v[206:207], v[30:31], v[222:223]
	v_lshl_add_u64 v[34:35], v[42:43], 2, s[96:97]
	v_lshl_add_u64 v[36:37], v[42:43], 1, s[6:7]
	global_store_dwordx4 v[34:35], v[28:31], off
	s_cbranch_vccnz .LBB0_449
	s_nop 0
	v_cvt_pk_bf16_f32 v28, v28, v29
	v_cvt_pk_bf16_f32 v29, v30, v31
	global_store_dwordx2 v[36:37], v[28:29], off
.LBB0_449:
	s_nop 0
	v_mov_b32_e32 v28, v33
	v_mov_b32_e32 v29, v33
	v_sub_f32_e32 v27, v27, v32
	v_sub_f32_e32 v26, v26, v32
	v_sub_f32_e32 v25, v25, v32
	v_sub_f32_e32 v24, v24, v32
	v_mov_b32_e32 v30, v33
	v_mov_b32_e32 v31, v33
	v_pk_mul_f32 v[24:25], v[28:29], v[24:25]
	v_pk_mul_f32 v[26:27], v[30:31], v[26:27]
	s_and_b64 vcc, exec, s[40:41]
	v_pk_fma_f32 v[26:27], v[26:27], v[210:211], v[226:227]
	v_pk_fma_f32 v[24:25], v[24:25], v[208:209], v[224:225]
	global_store_dwordx4 v[34:35], v[24:27], off offset:64
	s_cbranch_vccnz .LBB0_451
	s_nop 0
	v_cvt_pk_bf16_f32 v24, v24, v25
	v_cvt_pk_bf16_f32 v25, v26, v27
	global_store_dwordx2 v[36:37], v[24:25], off offset:32
.LBB0_451:
	s_nop 0
	v_sub_f32_e32 v23, v23, v32
	v_sub_f32_e32 v22, v22, v32
	v_sub_f32_e32 v21, v21, v32
	v_sub_f32_e32 v20, v20, v32
	v_pk_mul_f32 v[20:21], v[28:29], v[20:21]
	v_pk_mul_f32 v[22:23], v[30:31], v[22:23]
	s_and_b64 vcc, exec, s[40:41]
	v_pk_fma_f32 v[22:23], v[22:23], v[214:215], v[230:231]
	v_pk_fma_f32 v[20:21], v[20:21], v[212:213], v[228:229]
	global_store_dwordx4 v[34:35], v[20:23], off offset:512
	s_cbranch_vccnz .LBB0_453
	s_nop 0
	v_cvt_pk_bf16_f32 v20, v20, v21
	v_cvt_pk_bf16_f32 v21, v22, v23
	global_store_dwordx2 v[36:37], v[20:21], off offset:256
.LBB0_453:
	s_nop 0
	v_sub_f32_e32 v19, v19, v32
	v_sub_f32_e32 v18, v18, v32
	v_sub_f32_e32 v17, v17, v32
	v_sub_f32_e32 v16, v16, v32
	v_mov_b32_e32 v32, v33
	v_pk_mul_f32 v[16:17], v[28:29], v[16:17]
	v_pk_mul_f32 v[18:19], v[32:33], v[18:19]
	s_and_b64 vcc, exec, s[40:41]
	v_pk_fma_f32 v[18:19], v[18:19], v[218:219], v[234:235]
	v_pk_fma_f32 v[16:17], v[16:17], v[216:217], v[232:233]
	global_store_dwordx4 v[34:35], v[16:19], off offset:576
	s_cbranch_vccnz .LBB0_455
	s_nop 0
	v_cvt_pk_bf16_f32 v16, v16, v17
	v_cvt_pk_bf16_f32 v17, v18, v19
	global_store_dwordx2 v[36:37], v[16:17], off offset:288
.LBB0_455:
	s_nop 0
	v_add_u32_e32 v18, s21, v160
	v_ashrrev_i32_e32 v19, 31, v18
	ds_read_b64 v[16:17], v169
	v_lshlrev_b64 v[26:27], 11, v[18:19]
	v_or_b32_e32 v26, v26, v153
	s_and_b64 vcc, exec, s[40:41]
	s_waitcnt lgkmcnt(0)
	v_sub_f32_e32 v15, v15, v16
	v_sub_f32_e32 v14, v14, v16
	v_sub_f32_e32 v13, v13, v16
	v_sub_f32_e32 v12, v12, v16
	v_pk_mul_f32 v[12:13], v[16:17], v[12:13] op_sel:[1,0]
	v_pk_mul_f32 v[14:15], v[16:17], v[14:15] op_sel:[1,0]
	v_pk_fma_f32 v[12:13], v[204:205], v[12:13], v[220:221]
	v_pk_fma_f32 v[14:15], v[206:207], v[14:15], v[222:223]
	v_lshl_add_u64 v[18:19], v[26:27], 2, s[96:97]
	v_lshl_add_u64 v[20:21], v[26:27], 1, s[6:7]
	global_store_dwordx4 v[18:19], v[12:15], off
	s_cbranch_vccnz .LBB0_457
	s_nop 0
	v_cvt_pk_bf16_f32 v12, v12, v13
	v_cvt_pk_bf16_f32 v13, v14, v15
	global_store_dwordx2 v[20:21], v[12:13], off
.LBB0_457:
	s_nop 0
	v_mov_b32_e32 v12, v17
	v_mov_b32_e32 v13, v17
	v_sub_f32_e32 v11, v11, v16
	v_sub_f32_e32 v10, v10, v16
	v_sub_f32_e32 v9, v9, v16
	v_sub_f32_e32 v8, v8, v16
	v_mov_b32_e32 v14, v17
	v_mov_b32_e32 v15, v17
	v_pk_mul_f32 v[8:9], v[12:13], v[8:9]
	v_pk_mul_f32 v[10:11], v[14:15], v[10:11]
	s_and_b64 vcc, exec, s[40:41]
	v_pk_fma_f32 v[10:11], v[10:11], v[210:211], v[226:227]
	v_pk_fma_f32 v[8:9], v[8:9], v[208:209], v[224:225]
	global_store_dwordx4 v[18:19], v[8:11], off offset:64
	s_cbranch_vccnz .LBB0_459
	s_nop 0
	v_cvt_pk_bf16_f32 v8, v8, v9
	v_cvt_pk_bf16_f32 v9, v10, v11
	global_store_dwordx2 v[20:21], v[8:9], off offset:32
.LBB0_459:
	s_nop 0
	v_sub_f32_e32 v7, v7, v16
	v_sub_f32_e32 v6, v6, v16
	v_sub_f32_e32 v5, v5, v16
	v_sub_f32_e32 v4, v4, v16
	v_pk_mul_f32 v[4:5], v[12:13], v[4:5]
	v_pk_mul_f32 v[6:7], v[14:15], v[6:7]
	s_and_b64 vcc, exec, s[40:41]
	v_pk_fma_f32 v[6:7], v[6:7], v[214:215], v[230:231]
	v_pk_fma_f32 v[4:5], v[4:5], v[212:213], v[228:229]
	global_store_dwordx4 v[18:19], v[4:7], off offset:512
	s_cbranch_vccnz .LBB0_461
	s_nop 0
	v_cvt_pk_bf16_f32 v4, v4, v5
	v_cvt_pk_bf16_f32 v5, v6, v7
	global_store_dwordx2 v[20:21], v[4:5], off offset:256
.LBB0_461:
	s_nop 0
	v_sub_f32_e32 v3, v3, v16
	v_sub_f32_e32 v2, v2, v16
	v_sub_f32_e32 v1, v1, v16
	v_sub_f32_e32 v0, v0, v16
	v_mov_b32_e32 v16, v17
	v_pk_mul_f32 v[0:1], v[12:13], v[0:1]
	v_pk_mul_f32 v[2:3], v[16:17], v[2:3]
	s_and_b64 vcc, exec, s[40:41]
	v_pk_fma_f32 v[2:3], v[2:3], v[218:219], v[234:235]
	v_pk_fma_f32 v[0:1], v[0:1], v[216:217], v[232:233]
	global_store_dwordx4 v[18:19], v[0:3], off offset:576
	s_cbranch_vccnz .LBB0_463
	s_nop 0
	v_cvt_pk_bf16_f32 v0, v0, v1
	v_cvt_pk_bf16_f32 v1, v2, v3
	global_store_dwordx2 v[20:21], v[0:1], off offset:288

;     __device__ __forceinline__ void operator()(f32x4 (&acc)[2][2][4][2], const Unit& u, int wr, int wc, int fr, int fq, LAS unsigned char* lds) const {
;     ...
;             for (int m = 0; m < 4; ++m) { float sv = 0.f, qv = 0.f;
; #pragma unroll
;                 for (int bj = 0; bj < 2; ++bj)
; #pragma unroll
;                     for (int n = 0; n < 2; ++n) { const f32x4 x = acc[ai][bj][m][n]; sv += (x[0] + x[1]) + (x[2] + x[3]); qv += (x[0] * x[0] + x[1] * x[1]) + (x[2] * x[2] + x[3] * x[3]); }
;                 sv += __shfl_xor(sv, 16); sv += __shfl_xor(sv, 32); qv += __shfl_xor(qv, 16); qv += __shfl_xor(qv, 32);
;                 if (fq == 0) P[(ai * HALF + wr * 64 + m * 16 + fr) * 4 + wc] = (f32x2){sv, qv};
;                 __builtin_amdgcn_sched_barrier(0); }
;     ...
;                     for (int n = 0; n < 2; ++n) { const f32x4 gn = *(const f32x4*)(gain + col0 + bj * HALF + n * 16), bs = *(const f32x4*)(bias + col0 + bj * HALF + n * 16);
.LBB0_477:
	global_load_dwordx4 v[210:213], v[132:133], off
	global_load_dwordx4 v[214:217], v[132:133], off offset:64
	global_load_dwordx4 v[218:221], v[132:133], off offset:512
	global_load_dwordx4 v[222:225], v[132:133], off offset:576
	global_load_dwordx4 v[226:229], v[134:135], off
	global_load_dwordx4 v[230:233], v[134:135], off offset:64
	global_load_dwordx4 v[234:237], v[134:135], off offset:512
	global_load_dwordx4 v[238:241], v[134:135], off offset:576
	v_and_b32_e32 v157, 64, v198
	v_xor_b32_e32 v156, 16, v198
	v_add_u32_e32 v181, 64, v157
	v_cmp_lt_i32_e32 vcc, v156, v181
	v_mul_f32_e32 v160, v122, v122
	v_add_f32_e32 v158, v126, v127
	v_cndmask_b32_e32 v156, v198, v156, vcc
	v_lshlrev_b32_e32 v161, 2, v156
	v_add_f32_e32 v156, v124, v125
	v_mul_f32_e32 v183, v124, v124
	v_mul_f32_e32 v185, v125, v125
	v_mul_f32_e32 v187, v126, v126
	v_mul_f32_e32 v189, v127, v127
	v_mul_f32_e32 v157, v120, v120
	v_mul_f32_e32 v159, v121, v121
	v_pk_fma_f32 v[190:191], v[122:123], v[122:123], v[160:161] op_sel_hi:[1,1,0]
	v_mov_b32_e32 v182, v120
	v_mov_b32_e32 v184, v121
	v_mov_b32_e32 v186, v122
	v_mov_b32_e32 v188, v123
	v_pk_add_f32 v[182:183], v[182:183], v[184:185]
	v_pk_add_f32 v[184:185], v[186:187], v[188:189]
	v_pk_add_f32 v[156:157], v[156:157], v[158:159]
	v_mov_b32_e32 v190, v177
	v_mul_f32_e32 v193, v116, v116
	v_mul_f32_e32 v195, v117, v117
	v_mul_f32_e32 v197, v118, v118
	v_mul_f32_e32 v201, v119, v119
	v_pk_add_f32 v[182:183], v[182:183], v[184:185]
	v_pk_add_f32 v[156:157], v[156:157], v[190:191]
	v_mov_b32_e32 v192, v116
	v_mov_b32_e32 v194, v117
	v_mov_b32_e32 v196, v118
	v_mov_b32_e32 v200, v119
	v_pk_add_f32 v[156:157], v[182:183], v[156:157]
	v_pk_add_f32 v[158:159], v[192:193], v[194:195]
	v_pk_add_f32 v[182:183], v[196:197], v[200:201]
	v_mul_f32_e32 v203, v112, v112
	v_mul_f32_e32 v205, v113, v113
	v_mul_f32_e32 v207, v114, v114
	v_mul_f32_e32 v209, v115, v115
	v_pk_add_f32 v[158:159], v[158:159], v[182:183]
	v_mov_b32_e32 v202, v112
	v_mov_b32_e32 v204, v113
	v_mov_b32_e32 v206, v114
	v_mov_b32_e32 v208, v115
	v_pk_add_f32 v[156:157], v[156:157], v[158:159]
	v_pk_add_f32 v[158:159], v[202:203], v[204:205]
	v_pk_add_f32 v[182:183], v[206:207], v[208:209]
	v_xor_b32_e32 v160, 32, v198
	v_pk_add_f32 v[158:159], v[158:159], v[182:183]
	v_cmp_lt_i32_e32 vcc, v160, v181
	v_pk_add_f32 v[156:157], v[156:157], v[158:159]
	ds_bpermute_b32 v158, v161, v156
	ds_bpermute_b32 v159, v161, v157
	v_cndmask_b32_e32 v160, v198, v160, vcc
	v_lshlrev_b32_e32 v181, 2, v160
	v_mov_b32_e32 v160, v252
	s_waitcnt lgkmcnt(0)
	v_pk_add_f32 v[156:157], v[156:157], v[158:159]
	ds_bpermute_b32 v158, v181, v156
	ds_bpermute_b32 v159, v181, v157
	v_readfirstlane_b32 s19, v160
	s_and_saveexec_b64 s[38:39], s[36:37]
	s_cbranch_execz .LBB0_479
	s_waitcnt lgkmcnt(0)
	v_pk_add_f32 v[156:157], v[156:157], v[158:159]
	ds_write_b64 v180, v[156:157]

; __device__ __forceinline__ unsigned cvt_pk_bf16(float lo, float hi) { unsigned r; asm volatile("v_cvt_pk_bf16_f32 %0, %1, %2" : "=v"(r) : "v"(lo), "v"(hi)); return r; }
;     __device__ __forceinline__ void operator()(f32x4 (&acc)[2][2][4][2], const Unit& u, int wr, int wc, int fr, int fq, LAS unsigned char* lds) const {
;     ...
; #pragma unroll
;         for (int ai = 0; ai < 2; ++ai)
; #pragma unroll
;             for (int m = 0; m < 4; ++m) { const int r = ai * HALF + wr * 64 + m * 16 + fr; const f32x2 sr = ST[r]; const size_t off = (size_t)(u.pm * BM + r) * DM + col0;
; #pragma unroll
;                 for (int bj = 0; bj < 2; ++bj)
; #pragma unroll
;                     for (int n = 0; n < 2; ++n) { const f32x4 gn = *(const f32x4*)(gain + col0 + bj * HALF + n * 16), bs = *(const f32x4*)(bias + col0 + bj * HALF + n * 16);
;                         const f32x4 o = (acc[ai][bj][m][n] - sr.x) * sr.y * gn + bs; *(f32x4*)(out + off + bj * HALF + n * 16) = o;
;                         if (write_xb) { u32x2 w; w.x = cvt_pk_bf16(o[0], o[1]); w.y = cvt_pk_bf16(o[2], o[3]); *(u32x2*)(xb + off + bj * HALF + n * 16) = w; }
;                         __builtin_amdgcn_sched_barrier(0); }
;                 asm volatile("" ::: "memory"); }
.LBB0_507:
	s_or_b64 exec, exec, s[74:75]
	s_waitcnt lgkmcnt(0)
	v_add_u32_e32 v158, s18, v162
	s_waitcnt lgkmcnt(0)
	s_barrier
	v_lshl_add_u32 v156, v162, 3, s13
	v_ashrrev_i32_e32 v159, 31, v158
	ds_read_b64 v[156:157], v156
	v_lshlrev_b64 v[186:187], 11, v[158:159]
	v_or_b32_e32 v186, v186, v130
	s_andn2_b64 vcc, exec, s[42:43]
	s_waitcnt lgkmcnt(0)
	v_sub_f32_e32 v127, v127, v156
	v_sub_f32_e32 v126, v126, v156
	v_sub_f32_e32 v125, v125, v156
	v_sub_f32_e32 v124, v124, v156
	v_pk_mul_f32 v[126:127], v[156:157], v[126:127] op_sel:[1,0]
	v_pk_mul_f32 v[124:125], v[156:157], v[124:125] op_sel:[1,0]
	v_pk_fma_f32 v[126:127], v[212:213], v[126:127], v[228:229]
	v_cndmask_b32_e64 v160, 0, 1, s[42:43]
	v_pk_fma_f32 v[124:125], v[210:211], v[124:125], v[226:227]
	v_lshl_add_u64 v[158:159], v[186:187], 2, s[96:97]
	v_cmp_ne_u32_e64 s[38:39], 1, v160
	v_lshl_add_u64 v[160:161], v[186:187], 1, s[6:7]
	global_store_dwordx4 v[158:159], v[124:127], off
	s_cbranch_vccnz .LBB0_509
	s_nop 0
	v_cvt_pk_bf16_f32 v124, v124, v125
	v_cvt_pk_bf16_f32 v125, v126, v127
	global_store_dwordx2 v[160:161], v[124:125], off
.LBB0_509:
	s_nop 0
	v_mov_b32_e32 v124, v157
	v_mov_b32_e32 v125, v157
	v_sub_f32_e32 v123, v123, v156
	v_sub_f32_e32 v122, v122, v156
	v_sub_f32_e32 v121, v121, v156
	v_sub_f32_e32 v120, v120, v156
	v_mov_b32_e32 v126, v157
	v_mov_b32_e32 v127, v157
	v_pk_mul_f32 v[120:121], v[124:125], v[120:121]
	v_pk_mul_f32 v[122:123], v[126:127], v[122:123]
	s_and_b64 vcc, exec, s[38:39]
	v_pk_fma_f32 v[122:123], v[122:123], v[216:217], v[232:233]
	v_pk_fma_f32 v[120:121], v[120:121], v[214:215], v[230:231]
	global_store_dwordx4 v[158:159], v[120:123], off offset:64
	s_cbranch_vccnz .LBB0_511
	s_nop 0
	v_cvt_pk_bf16_f32 v120, v120, v121
	v_cvt_pk_bf16_f32 v121, v122, v123
	global_store_dwordx2 v[160:161], v[120:121], off offset:32
.LBB0_511:
	s_nop 0
	v_sub_f32_e32 v119, v119, v156
	v_sub_f32_e32 v118, v118, v156
	v_sub_f32_e32 v117, v117, v156
	v_sub_f32_e32 v116, v116, v156
	v_pk_mul_f32 v[116:117], v[124:125], v[116:117]
	v_pk_mul_f32 v[118:119], v[126:127], v[118:119]
	s_and_b64 vcc, exec, s[38:39]
	v_pk_fma_f32 v[118:119], v[118:119], v[220:221], v[236:237]
	v_pk_fma_f32 v[116:117], v[116:117], v[218:219], v[234:235]
	global_store_dwordx4 v[158:159], v[116:119], off offset:512
	s_cbranch_vccnz .LBB0_513
	s_nop 0
	v_cvt_pk_bf16_f32 v116, v116, v117
	v_cvt_pk_bf16_f32 v117, v118, v119
	global_store_dwordx2 v[160:161], v[116:117], off offset:256
.LBB0_513:
	s_nop 0
	v_sub_f32_e32 v115, v115, v156
	v_sub_f32_e32 v114, v114, v156
	v_sub_f32_e32 v113, v113, v156
	v_sub_f32_e32 v112, v112, v156
	v_mov_b32_e32 v156, v157
	v_pk_mul_f32 v[112:113], v[124:125], v[112:113]
	v_pk_mul_f32 v[114:115], v[156:157], v[114:115]
	s_and_b64 vcc, exec, s[38:39]
	v_pk_fma_f32 v[114:115], v[114:115], v[224:225], v[240:241]
	v_pk_fma_f32 v[112:113], v[112:113], v[222:223], v[238:239]
	global_store_dwordx4 v[158:159], v[112:115], off offset:576
	s_cbranch_vccnz .LBB0_515
	s_nop 0
	v_cvt_pk_bf16_f32 v112, v112, v113
	v_cvt_pk_bf16_f32 v113, v114, v115
	global_store_dwordx2 v[160:161], v[112:113], off offset:288
.LBB0_515:
	s_nop 0
	v_add_u32_e32 v114, s18, v163
	v_ashrrev_i32_e32 v115, 31, v114
	ds_read_b64 v[112:113], v131
	v_lshlrev_b64 v[122:123], 11, v[114:115]
	v_or_b32_e32 v122, v122, v130
	s_and_b64 vcc, exec, s[38:39]
	s_waitcnt lgkmcnt(0)
	v_sub_f32_e32 v111, v111, v112
	v_sub_f32_e32 v110, v110, v112
	v_sub_f32_e32 v109, v109, v112
	v_sub_f32_e32 v108, v108, v112
	v_pk_mul_f32 v[108:109], v[112:113], v[108:109] op_sel:[1,0]
	v_pk_mul_f32 v[110:111], v[112:113], v[110:111] op_sel:[1,0]
	v_pk_fma_f32 v[108:109], v[210:211], v[108:109], v[226:227]
	v_pk_fma_f32 v[110:111], v[212:213], v[110:111], v[228:229]
	v_lshl_add_u64 v[114:115], v[122:123], 2, s[96:97]
	v_lshl_add_u64 v[116:117], v[122:123], 1, s[6:7]
	global_store_dwordx4 v[114:115], v[108:111], off
	s_cbranch_vccnz .LBB0_517
	s_nop 0
	v_cvt_pk_bf16_f32 v108, v108, v109
	v_cvt_pk_bf16_f32 v109, v110, v111
	global_store_dwordx2 v[116:117], v[108:109], off
.LBB0_517:
	s_nop 0
	v_mov_b32_e32 v108, v113
	v_mov_b32_e32 v109, v113
	v_sub_f32_e32 v107, v107, v112
	v_sub_f32_e32 v106, v106, v112
	v_sub_f32_e32 v105, v105, v112
	v_sub_f32_e32 v104, v104, v112
	v_mov_b32_e32 v110, v113
	v_mov_b32_e32 v111, v113
	v_pk_mul_f32 v[104:105], v[108:109], v[104:105]
	v_pk_mul_f32 v[106:107], v[110:111], v[106:107]
	s_and_b64 vcc, exec, s[38:39]
	v_pk_fma_f32 v[106:107], v[106:107], v[216:217], v[232:233]
	v_pk_fma_f32 v[104:105], v[104:105], v[214:215], v[230:231]
	global_store_dwordx4 v[114:115], v[104:107], off offset:64
	s_cbranch_vccnz .LBB0_519
	s_nop 0
	v_cvt_pk_bf16_f32 v104, v104, v105
	v_cvt_pk_bf16_f32 v105, v106, v107
	global_store_dwordx2 v[116:117], v[104:105], off offset:32
.LBB0_519:
	s_nop 0
	v_sub_f32_e32 v103, v103, v112
	v_sub_f32_e32 v102, v102, v112
	v_sub_f32_e32 v101, v101, v112
	v_sub_f32_e32 v100, v100, v112
	v_pk_mul_f32 v[100:101], v[108:109], v[100:101]
	v_pk_mul_f32 v[102:103], v[110:111], v[102:103]
	s_and_b64 vcc, exec, s[38:39]
	v_pk_fma_f32 v[102:103], v[102:103], v[220:221], v[236:237]
	v_pk_fma_f32 v[100:101], v[100:101], v[218:219], v[234:235]
	global_store_dwordx4 v[114:115], v[100:103], off offset:512
	s_cbranch_vccnz .LBB0_521
	s_nop 0
	v_cvt_pk_bf16_f32 v100, v100, v101
	v_cvt_pk_bf16_f32 v101, v102, v103
	global_store_dwordx2 v[116:117], v[100:101], off offset:256
; __device__ __forceinline__ unsigned cvt_pk_bf16(float lo, float hi) { unsigned r; asm volatile("v_cvt_pk_bf16_f32 %0, %1, %2" : "=v"(r) : "v"(lo), "v"(hi)); return r; }
;     __device__ __forceinline__ void operator()(f32x4 (&acc)[2][2][4][2], const Unit& u, int wr, int wc, int fr, int fq, LAS unsigned char* lds) const {
;     ...
; #pragma unroll
;         for (int ai = 0; ai < 2; ++ai)
; #pragma unroll
;             for (int m = 0; m < 4; ++m) { const int r = ai * HALF + wr * 64 + m * 16 + fr; const f32x2 sr = ST[r]; const size_t off = (size_t)(u.pm * BM + r) * DM + col0;
; #pragma unroll
;                 for (int bj = 0; bj < 2; ++bj)
; #pragma unroll
;                     for (int n = 0; n < 2; ++n) { const f32x4 gn = *(const f32x4*)(gain + col0 + bj * HALF + n * 16), bs = *(const f32x4*)(bias + col0 + bj * HALF + n * 16);
;                         const f32x4 o = (acc[ai][bj][m][n] - sr.x) * sr.y * gn + bs; *(f32x4*)(out + off + bj * HALF + n * 16) = o;
;                         if (write_xb) { u32x2 w; w.x = cvt_pk_bf16(o[0], o[1]); w.y = cvt_pk_bf16(o[2], o[3]); *(u32x2*)(xb + off + bj * HALF + n * 16) = w; }
;                         __builtin_amdgcn_sched_barrier(0); }
;                 asm volatile("" ::: "memory"); }
.LBB0_521:
	s_nop 0
	v_sub_f32_e32 v99, v99, v112
	v_sub_f32_e32 v98, v98, v112
	v_sub_f32_e32 v97, v97, v112
	v_sub_f32_e32 v96, v96, v112
	v_mov_b32_e32 v112, v113
	v_pk_mul_f32 v[96:97], v[108:109], v[96:97]
	v_pk_mul_f32 v[98:99], v[112:113], v[98:99]
	s_and_b64 vcc, exec, s[38:39]
	v_pk_fma_f32 v[98:99], v[98:99], v[224:225], v[240:241]
	v_pk_fma_f32 v[96:97], v[96:97], v[222:223], v[238:239]
	global_store_dwordx4 v[114:115], v[96:99], off offset:576
	s_cbranch_vccnz .LBB0_523
	s_nop 0
	v_cvt_pk_bf16_f32 v96, v96, v97
	v_cvt_pk_bf16_f32 v97, v98, v99
	global_store_dwordx2 v[116:117], v[96:97], off offset:288
.LBB0_523:
	s_nop 0
	v_add_u32_e32 v98, s18, v164
	v_ashrrev_i32_e32 v99, 31, v98
	ds_read_b64 v[96:97], v171
	v_lshlrev_b64 v[106:107], 11, v[98:99]
	v_or_b32_e32 v106, v106, v130
	s_and_b64 vcc, exec, s[38:39]
	s_waitcnt lgkmcnt(0)
	v_sub_f32_e32 v95, v95, v96
	v_sub_f32_e32 v94, v94, v96
	v_sub_f32_e32 v93, v93, v96
	v_sub_f32_e32 v92, v92, v96
	v_pk_mul_f32 v[92:93], v[96:97], v[92:93] op_sel:[1,0]
	v_pk_mul_f32 v[94:95], v[96:97], v[94:95] op_sel:[1,0]
	v_pk_fma_f32 v[92:93], v[210:211], v[92:93], v[226:227]
	v_pk_fma_f32 v[94:95], v[212:213], v[94:95], v[228:229]
	v_lshl_add_u64 v[98:99], v[106:107], 2, s[96:97]
	v_lshl_add_u64 v[100:101], v[106:107], 1, s[6:7]
	global_store_dwordx4 v[98:99], v[92:95], off
	s_cbranch_vccnz .LBB0_525
	s_nop 0
	v_cvt_pk_bf16_f32 v92, v92, v93
	v_cvt_pk_bf16_f32 v93, v94, v95
	global_store_dwordx2 v[100:101], v[92:93], off
.LBB0_525:
	s_nop 0
	v_mov_b32_e32 v92, v97
	v_mov_b32_e32 v93, v97
	v_sub_f32_e32 v91, v91, v96
	v_sub_f32_e32 v90, v90, v96
	v_sub_f32_e32 v89, v89, v96
	v_sub_f32_e32 v88, v88, v96
	v_mov_b32_e32 v94, v97
	v_mov_b32_e32 v95, v97
	v_pk_mul_f32 v[88:89], v[92:93], v[88:89]
	v_pk_mul_f32 v[90:91], v[94:95], v[90:91]
	s_and_b64 vcc, exec, s[38:39]
	v_pk_fma_f32 v[90:91], v[90:91], v[216:217], v[232:233]
	v_pk_fma_f32 v[88:89], v[88:89], v[214:215], v[230:231]
	global_store_dwordx4 v[98:99], v[88:91], off offset:64
	s_cbranch_vccnz .LBB0_527
	s_nop 0
	v_cvt_pk_bf16_f32 v88, v88, v89
	v_cvt_pk_bf16_f32 v89, v90, v91
	global_store_dwordx2 v[100:101], v[88:89], off offset:32
.LBB0_527:
	s_nop 0
	v_sub_f32_e32 v87, v87, v96
	v_sub_f32_e32 v86, v86, v96
	v_sub_f32_e32 v85, v85, v96
	v_sub_f32_e32 v84, v84, v96
	v_pk_mul_f32 v[84:85], v[92:93], v[84:85]
	v_pk_mul_f32 v[86:87], v[94:95], v[86:87]
	s_and_b64 vcc, exec, s[38:39]
	v_pk_fma_f32 v[86:87], v[86:87], v[220:221], v[236:237]
	v_pk_fma_f32 v[84:85], v[84:85], v[218:219], v[234:235]
	global_store_dwordx4 v[98:99], v[84:87], off offset:512
	s_cbranch_vccnz .LBB0_529
	s_nop 0
	v_cvt_pk_bf16_f32 v84, v84, v85
	v_cvt_pk_bf16_f32 v85, v86, v87
	global_store_dwordx2 v[100:101], v[84:85], off offset:256
.LBB0_529:
	s_nop 0
	v_sub_f32_e32 v83, v83, v96
	v_sub_f32_e32 v82, v82, v96
	v_sub_f32_e32 v81, v81, v96
	v_sub_f32_e32 v80, v80, v96
	v_mov_b32_e32 v96, v97
	v_pk_mul_f32 v[80:81], v[92:93], v[80:81]
	v_pk_mul_f32 v[82:83], v[96:97], v[82:83]
	s_and_b64 vcc, exec, s[38:39]
	v_pk_fma_f32 v[82:83], v[82:83], v[224:225], v[240:241]
	v_pk_fma_f32 v[80:81], v[80:81], v[222:223], v[238:239]
	global_store_dwordx4 v[98:99], v[80:83], off offset:576
	s_cbranch_vccnz .LBB0_531
	s_nop 0
	v_cvt_pk_bf16_f32 v80, v80, v81
	v_cvt_pk_bf16_f32 v81, v82, v83
	global_store_dwordx2 v[100:101], v[80:81], off offset:288
.LBB0_531:
	s_nop 0
	v_add_u32_e32 v82, s18, v165
	v_ashrrev_i32_e32 v83, 31, v82
	ds_read_b64 v[80:81], v172
	v_lshlrev_b64 v[90:91], 11, v[82:83]
	v_or_b32_e32 v90, v90, v130
	s_and_b64 vcc, exec, s[38:39]
	s_waitcnt lgkmcnt(0)
	v_sub_f32_e32 v79, v79, v80
	v_sub_f32_e32 v78, v78, v80
	v_sub_f32_e32 v77, v77, v80
	v_sub_f32_e32 v76, v76, v80
	v_pk_mul_f32 v[76:77], v[80:81], v[76:77] op_sel:[1,0]
	v_pk_mul_f32 v[78:79], v[80:81], v[78:79] op_sel:[1,0]
	v_pk_fma_f32 v[76:77], v[210:211], v[76:77], v[226:227]
	v_pk_fma_f32 v[78:79], v[212:213], v[78:79], v[228:229]
	v_lshl_add_u64 v[82:83], v[90:91], 2, s[96:97]
	v_lshl_add_u64 v[84:85], v[90:91], 1, s[6:7]
	global_store_dwordx4 v[82:83], v[76:79], off
	s_cbranch_vccnz .LBB0_533
	s_nop 0
	v_cvt_pk_bf16_f32 v76, v76, v77
	v_cvt_pk_bf16_f32 v77, v78, v79
	global_store_dwordx2 v[84:85], v[76:77], off
.LBB0_533:
	s_nop 0
	v_mov_b32_e32 v76, v81
	v_mov_b32_e32 v77, v81
	v_sub_f32_e32 v75, v75, v80
	v_sub_f32_e32 v74, v74, v80
	v_sub_f32_e32 v73, v73, v80
	v_sub_f32_e32 v72, v72, v80
	v_mov_b32_e32 v78, v81
	v_mov_b32_e32 v79, v81
	v_pk_mul_f32 v[72:73], v[76:77], v[72:73]
	v_pk_mul_f32 v[74:75], v[78:79], v[74:75]
	s_and_b64 vcc, exec, s[38:39]
	v_pk_fma_f32 v[74:75], v[74:75], v[216:217], v[232:233]
	v_pk_fma_f32 v[72:73], v[72:73], v[214:215], v[230:231]
	global_store_dwordx4 v[82:83], v[72:75], off offset:64
	s_cbranch_vccnz .LBB0_535
	s_nop 0
	v_cvt_pk_bf16_f32 v72, v72, v73
	v_cvt_pk_bf16_f32 v73, v74, v75
	global_store_dwordx2 v[84:85], v[72:73], off offset:32
.LBB0_535:
	s_nop 0
	v_sub_f32_e32 v71, v71, v80
	v_sub_f32_e32 v70, v70, v80
	v_sub_f32_e32 v69, v69, v80
	v_sub_f32_e32 v68, v68, v80
	v_pk_mul_f32 v[68:69], v[76:77], v[68:69]
	v_pk_mul_f32 v[70:71], v[78:79], v[70:71]
	s_and_b64 vcc, exec, s[38:39]
	v_pk_fma_f32 v[70:71], v[70:71], v[220:221], v[236:237]
	v_pk_fma_f32 v[68:69], v[68:69], v[218:219], v[234:235]
	global_store_dwordx4 v[82:83], v[68:71], off offset:512
	s_cbranch_vccnz .LBB0_537
	s_nop 0
	v_cvt_pk_bf16_f32 v68, v68, v69
	v_cvt_pk_bf16_f32 v69, v70, v71
	global_store_dwordx2 v[84:85], v[68:69], off offset:256
; __device__ __forceinline__ unsigned cvt_pk_bf16(float lo, float hi) { unsigned r; asm volatile("v_cvt_pk_bf16_f32 %0, %1, %2" : "=v"(r) : "v"(lo), "v"(hi)); return r; }
;     __device__ __forceinline__ void operator()(f32x4 (&acc)[2][2][4][2], const Unit& u, int wr, int wc, int fr, int fq, LAS unsigned char* lds) const {
;     ...
; #pragma unroll
;         for (int ai = 0; ai < 2; ++ai)
; #pragma unroll
;             for (int m = 0; m < 4; ++m) { const int r = ai * HALF + wr * 64 + m * 16 + fr; const f32x2 sr = ST[r]; const size_t off = (size_t)(u.pm * BM + r) * DM + col0;
; #pragma unroll
;                 for (int bj = 0; bj < 2; ++bj)
; #pragma unroll
;                     for (int n = 0; n < 2; ++n) { const f32x4 gn = *(const f32x4*)(gain + col0 + bj * HALF + n * 16), bs = *(const f32x4*)(bias + col0 + bj * HALF + n * 16);
;                         const f32x4 o = (acc[ai][bj][m][n] - sr.x) * sr.y * gn + bs; *(f32x4*)(out + off + bj * HALF + n * 16) = o;
;                         if (write_xb) { u32x2 w; w.x = cvt_pk_bf16(o[0], o[1]); w.y = cvt_pk_bf16(o[2], o[3]); *(u32x2*)(xb + off + bj * HALF + n * 16) = w; }
;                         __builtin_amdgcn_sched_barrier(0); }
;                 asm volatile("" ::: "memory"); }
.LBB0_537:
	s_nop 0
	v_sub_f32_e32 v67, v67, v80
	v_sub_f32_e32 v66, v66, v80
	v_sub_f32_e32 v65, v65, v80
	v_sub_f32_e32 v64, v64, v80
	v_mov_b32_e32 v80, v81
	v_pk_mul_f32 v[64:65], v[76:77], v[64:65]
	v_pk_mul_f32 v[66:67], v[80:81], v[66:67]
	s_and_b64 vcc, exec, s[38:39]
	v_pk_fma_f32 v[66:67], v[66:67], v[224:225], v[240:241]
	v_pk_fma_f32 v[64:65], v[64:65], v[222:223], v[238:239]
	global_store_dwordx4 v[82:83], v[64:67], off offset:576
	s_cbranch_vccnz .LBB0_539
	s_nop 0
	v_cvt_pk_bf16_f32 v64, v64, v65
	v_cvt_pk_bf16_f32 v65, v66, v67
	global_store_dwordx2 v[84:85], v[64:65], off offset:288
.LBB0_539:
	s_nop 0
	v_add_u32_e32 v66, s18, v166
	v_ashrrev_i32_e32 v67, 31, v66
	ds_read_b64 v[64:65], v173
	v_lshlrev_b64 v[74:75], 11, v[66:67]
	v_or_b32_e32 v74, v74, v130
	s_and_b64 vcc, exec, s[38:39]
	s_waitcnt lgkmcnt(0)
	v_sub_f32_e32 v63, v63, v64
	v_sub_f32_e32 v62, v62, v64
	v_sub_f32_e32 v61, v61, v64
	v_sub_f32_e32 v60, v60, v64
	v_pk_mul_f32 v[60:61], v[64:65], v[60:61] op_sel:[1,0]
	v_pk_mul_f32 v[62:63], v[64:65], v[62:63] op_sel:[1,0]
	v_pk_fma_f32 v[60:61], v[210:211], v[60:61], v[226:227]
	v_pk_fma_f32 v[62:63], v[212:213], v[62:63], v[228:229]
	v_lshl_add_u64 v[66:67], v[74:75], 2, s[96:97]
	v_lshl_add_u64 v[68:69], v[74:75], 1, s[6:7]
	global_store_dwordx4 v[66:67], v[60:63], off
	s_cbranch_vccnz .LBB0_541
	s_nop 0
	v_cvt_pk_bf16_f32 v60, v60, v61
	v_cvt_pk_bf16_f32 v61, v62, v63
	global_store_dwordx2 v[68:69], v[60:61], off
.LBB0_541:
	s_nop 0
	v_mov_b32_e32 v60, v65
	v_mov_b32_e32 v61, v65
	v_sub_f32_e32 v59, v59, v64
	v_sub_f32_e32 v58, v58, v64
	v_sub_f32_e32 v57, v57, v64
	v_sub_f32_e32 v56, v56, v64
	v_mov_b32_e32 v62, v65
	v_mov_b32_e32 v63, v65
	v_pk_mul_f32 v[56:57], v[60:61], v[56:57]
	v_pk_mul_f32 v[58:59], v[62:63], v[58:59]
	s_and_b64 vcc, exec, s[38:39]
	v_pk_fma_f32 v[58:59], v[58:59], v[216:217], v[232:233]
	v_pk_fma_f32 v[56:57], v[56:57], v[214:215], v[230:231]
	global_store_dwordx4 v[66:67], v[56:59], off offset:64
	s_cbranch_vccnz .LBB0_543
	s_nop 0
	v_cvt_pk_bf16_f32 v56, v56, v57
	v_cvt_pk_bf16_f32 v57, v58, v59
	global_store_dwordx2 v[68:69], v[56:57], off offset:32
.LBB0_543:
	s_nop 0
	v_sub_f32_e32 v55, v55, v64
	v_sub_f32_e32 v54, v54, v64
	v_sub_f32_e32 v53, v53, v64
	v_sub_f32_e32 v52, v52, v64
	v_pk_mul_f32 v[52:53], v[60:61], v[52:53]
	v_pk_mul_f32 v[54:55], v[62:63], v[54:55]
	s_and_b64 vcc, exec, s[38:39]
	v_pk_fma_f32 v[54:55], v[54:55], v[220:221], v[236:237]
	v_pk_fma_f32 v[52:53], v[52:53], v[218:219], v[234:235]
	global_store_dwordx4 v[66:67], v[52:55], off offset:512
	s_cbranch_vccnz .LBB0_545
	s_nop 0
	v_cvt_pk_bf16_f32 v52, v52, v53
	v_cvt_pk_bf16_f32 v53, v54, v55
	global_store_dwordx2 v[68:69], v[52:53], off offset:256
.LBB0_545:
	s_nop 0
	v_sub_f32_e32 v51, v51, v64
	v_sub_f32_e32 v50, v50, v64
	v_sub_f32_e32 v49, v49, v64
	v_sub_f32_e32 v48, v48, v64
	v_mov_b32_e32 v64, v65
	v_pk_mul_f32 v[48:49], v[60:61], v[48:49]
	v_pk_mul_f32 v[50:51], v[64:65], v[50:51]
	s_and_b64 vcc, exec, s[38:39]
	v_pk_fma_f32 v[50:51], v[50:51], v[224:225], v[240:241]
	v_pk_fma_f32 v[48:49], v[48:49], v[222:223], v[238:239]
	global_store_dwordx4 v[66:67], v[48:51], off offset:576
	s_cbranch_vccnz .LBB0_547
	s_nop 0
	v_cvt_pk_bf16_f32 v48, v48, v49
	v_cvt_pk_bf16_f32 v49, v50, v51
	global_store_dwordx2 v[68:69], v[48:49], off offset:288
.LBB0_547:
	s_nop 0
	v_add_u32_e32 v50, s18, v167
	v_ashrrev_i32_e32 v51, 31, v50
	ds_read_b64 v[48:49], v174
	v_lshlrev_b64 v[58:59], 11, v[50:51]
	v_or_b32_e32 v58, v58, v130
	s_and_b64 vcc, exec, s[38:39]
	s_waitcnt lgkmcnt(0)
	v_sub_f32_e32 v47, v47, v48
	v_sub_f32_e32 v46, v46, v48
	v_sub_f32_e32 v45, v45, v48
	v_sub_f32_e32 v44, v44, v48
	v_pk_mul_f32 v[44:45], v[48:49], v[44:45] op_sel:[1,0]
	v_pk_mul_f32 v[46:47], v[48:49], v[46:47] op_sel:[1,0]
	v_pk_fma_f32 v[44:45], v[210:211], v[44:45], v[226:227]
	v_pk_fma_f32 v[46:47], v[212:213], v[46:47], v[228:229]
	v_lshl_add_u64 v[50:51], v[58:59], 2, s[96:97]
	v_lshl_add_u64 v[52:53], v[58:59], 1, s[6:7]
	global_store_dwordx4 v[50:51], v[44:47], off
	s_cbranch_vccnz .LBB0_549
	s_nop 0
	v_cvt_pk_bf16_f32 v44, v44, v45
	v_cvt_pk_bf16_f32 v45, v46, v47
	global_store_dwordx2 v[52:53], v[44:45], off
.LBB0_549:
	s_nop 0
	v_mov_b32_e32 v44, v49
	v_mov_b32_e32 v45, v49
	v_sub_f32_e32 v43, v43, v48
	v_sub_f32_e32 v42, v42, v48
	v_sub_f32_e32 v41, v41, v48
	v_sub_f32_e32 v40, v40, v48
	v_mov_b32_e32 v46, v49
	v_mov_b32_e32 v47, v49
	v_pk_mul_f32 v[40:41], v[44:45], v[40:41]
	v_pk_mul_f32 v[42:43], v[46:47], v[42:43]
	s_and_b64 vcc, exec, s[38:39]
	v_pk_fma_f32 v[42:43], v[42:43], v[216:217], v[232:233]
	v_pk_fma_f32 v[40:41], v[40:41], v[214:215], v[230:231]
	global_store_dwordx4 v[50:51], v[40:43], off offset:64
	s_cbranch_vccnz .LBB0_551
	s_nop 0
	v_cvt_pk_bf16_f32 v40, v40, v41
	v_cvt_pk_bf16_f32 v41, v42, v43
	global_store_dwordx2 v[52:53], v[40:41], off offset:32
.LBB0_551:
	s_nop 0
	v_sub_f32_e32 v39, v39, v48
	v_sub_f32_e32 v38, v38, v48
	v_sub_f32_e32 v37, v37, v48
	v_sub_f32_e32 v36, v36, v48
	v_pk_mul_f32 v[36:37], v[44:45], v[36:37]
	v_pk_mul_f32 v[38:39], v[46:47], v[38:39]
	s_and_b64 vcc, exec, s[38:39]
	v_pk_fma_f32 v[38:39], v[38:39], v[220:221], v[236:237]
	v_pk_fma_f32 v[36:37], v[36:37], v[218:219], v[234:235]
	global_store_dwordx4 v[50:51], v[36:39], off offset:512
	s_cbranch_vccnz .LBB0_553
	s_nop 0
	v_cvt_pk_bf16_f32 v36, v36, v37
	v_cvt_pk_bf16_f32 v37, v38, v39
	global_store_dwordx2 v[52:53], v[36:37], off offset:256
; __device__ __forceinline__ unsigned cvt_pk_bf16(float lo, float hi) { unsigned r; asm volatile("v_cvt_pk_bf16_f32 %0, %1, %2" : "=v"(r) : "v"(lo), "v"(hi)); return r; }
;     __device__ __forceinline__ void operator()(f32x4 (&acc)[2][2][4][2], const Unit& u, int wr, int wc, int fr, int fq, LAS unsigned char* lds) const {
;     ...
; #pragma unroll
;         for (int ai = 0; ai < 2; ++ai)
; #pragma unroll
;             for (int m = 0; m < 4; ++m) { const int r = ai * HALF + wr * 64 + m * 16 + fr; const f32x2 sr = ST[r]; const size_t off = (size_t)(u.pm * BM + r) * DM + col0;
; #pragma unroll
;                 for (int bj = 0; bj < 2; ++bj)
; #pragma unroll
;                     for (int n = 0; n < 2; ++n) { const f32x4 gn = *(const f32x4*)(gain + col0 + bj * HALF + n * 16), bs = *(const f32x4*)(bias + col0 + bj * HALF + n * 16);
;                         const f32x4 o = (acc[ai][bj][m][n] - sr.x) * sr.y * gn + bs; *(f32x4*)(out + off + bj * HALF + n * 16) = o;
;                         if (write_xb) { u32x2 w; w.x = cvt_pk_bf16(o[0], o[1]); w.y = cvt_pk_bf16(o[2], o[3]); *(u32x2*)(xb + off + bj * HALF + n * 16) = w; }
;                         __builtin_amdgcn_sched_barrier(0); }
;                 asm volatile("" ::: "memory"); }
.LBB0_553:
	s_nop 0
	v_sub_f32_e32 v35, v35, v48
	v_sub_f32_e32 v34, v34, v48
	v_sub_f32_e32 v33, v33, v48
	v_sub_f32_e32 v32, v32, v48
	v_mov_b32_e32 v48, v49
	v_pk_mul_f32 v[32:33], v[44:45], v[32:33]
	v_pk_mul_f32 v[34:35], v[48:49], v[34:35]
	s_and_b64 vcc, exec, s[38:39]
	v_pk_fma_f32 v[34:35], v[34:35], v[224:225], v[240:241]
	v_pk_fma_f32 v[32:33], v[32:33], v[222:223], v[238:239]
	global_store_dwordx4 v[50:51], v[32:35], off offset:576
	s_cbranch_vccnz .LBB0_555
	s_nop 0
	v_cvt_pk_bf16_f32 v32, v32, v33
	v_cvt_pk_bf16_f32 v33, v34, v35
	global_store_dwordx2 v[52:53], v[32:33], off offset:288
.LBB0_555:
	s_nop 0
	v_add_u32_e32 v34, s18, v168
	v_ashrrev_i32_e32 v35, 31, v34
	ds_read_b64 v[32:33], v175
	v_lshlrev_b64 v[42:43], 11, v[34:35]
	v_or_b32_e32 v42, v42, v130
	s_and_b64 vcc, exec, s[38:39]
	s_waitcnt lgkmcnt(0)
	v_sub_f32_e32 v31, v31, v32
	v_sub_f32_e32 v30, v30, v32
	v_sub_f32_e32 v29, v29, v32
	v_sub_f32_e32 v28, v28, v32
	v_pk_mul_f32 v[28:29], v[32:33], v[28:29] op_sel:[1,0]
	v_pk_mul_f32 v[30:31], v[32:33], v[30:31] op_sel:[1,0]
	v_pk_fma_f32 v[28:29], v[210:211], v[28:29], v[226:227]
	v_pk_fma_f32 v[30:31], v[212:213], v[30:31], v[228:229]
	v_lshl_add_u64 v[34:35], v[42:43], 2, s[96:97]
	v_lshl_add_u64 v[36:37], v[42:43], 1, s[6:7]
	global_store_dwordx4 v[34:35], v[28:31], off
	s_cbranch_vccnz .LBB0_557
	s_nop 0
	v_cvt_pk_bf16_f32 v28, v28, v29
	v_cvt_pk_bf16_f32 v29, v30, v31
	global_store_dwordx2 v[36:37], v[28:29], off
.LBB0_557:
	s_nop 0
	v_mov_b32_e32 v28, v33
	v_mov_b32_e32 v29, v33
	v_sub_f32_e32 v27, v27, v32
	v_sub_f32_e32 v26, v26, v32
	v_sub_f32_e32 v25, v25, v32
	v_sub_f32_e32 v24, v24, v32
	v_mov_b32_e32 v30, v33
	v_mov_b32_e32 v31, v33
	v_pk_mul_f32 v[24:25], v[28:29], v[24:25]
	v_pk_mul_f32 v[26:27], v[30:31], v[26:27]
	s_and_b64 vcc, exec, s[38:39]
	v_pk_fma_f32 v[26:27], v[26:27], v[216:217], v[232:233]
	v_pk_fma_f32 v[24:25], v[24:25], v[214:215], v[230:231]
	global_store_dwordx4 v[34:35], v[24:27], off offset:64
	s_cbranch_vccnz .LBB0_559
	s_nop 0
	v_cvt_pk_bf16_f32 v24, v24, v25
	v_cvt_pk_bf16_f32 v25, v26, v27
	global_store_dwordx2 v[36:37], v[24:25], off offset:32
.LBB0_559:
	s_nop 0
	v_sub_f32_e32 v23, v23, v32
	v_sub_f32_e32 v22, v22, v32
	v_sub_f32_e32 v21, v21, v32
	v_sub_f32_e32 v20, v20, v32
	v_pk_mul_f32 v[20:21], v[28:29], v[20:21]
	v_pk_mul_f32 v[22:23], v[30:31], v[22:23]
	s_and_b64 vcc, exec, s[38:39]
	v_pk_fma_f32 v[22:23], v[22:23], v[220:221], v[236:237]
	v_pk_fma_f32 v[20:21], v[20:21], v[218:219], v[234:235]
	global_store_dwordx4 v[34:35], v[20:23], off offset:512
	s_cbranch_vccnz .LBB0_561
	s_nop 0
	v_cvt_pk_bf16_f32 v20, v20, v21
	v_cvt_pk_bf16_f32 v21, v22, v23
	global_store_dwordx2 v[36:37], v[20:21], off offset:256
.LBB0_561:
	s_nop 0
	v_sub_f32_e32 v19, v19, v32
	v_sub_f32_e32 v18, v18, v32
	v_sub_f32_e32 v17, v17, v32
	v_sub_f32_e32 v16, v16, v32
	v_mov_b32_e32 v32, v33
	v_pk_mul_f32 v[16:17], v[28:29], v[16:17]
	v_pk_mul_f32 v[18:19], v[32:33], v[18:19]
	s_and_b64 vcc, exec, s[38:39]
	v_pk_fma_f32 v[18:19], v[18:19], v[224:225], v[240:241]
	v_pk_fma_f32 v[16:17], v[16:17], v[222:223], v[238:239]
	global_store_dwordx4 v[34:35], v[16:19], off offset:576
	s_cbranch_vccnz .LBB0_563
	s_nop 0
	v_cvt_pk_bf16_f32 v16, v16, v17
	v_cvt_pk_bf16_f32 v17, v18, v19
	global_store_dwordx2 v[36:37], v[16:17], off offset:288
.LBB0_563:
	s_nop 0
	v_add_u32_e32 v18, s18, v169
	v_ashrrev_i32_e32 v19, 31, v18
	ds_read_b64 v[16:17], v178
	v_lshlrev_b64 v[26:27], 11, v[18:19]
	v_or_b32_e32 v26, v26, v130
	s_and_b64 vcc, exec, s[38:39]
	s_waitcnt lgkmcnt(0)
	v_sub_f32_e32 v15, v15, v16
	v_sub_f32_e32 v14, v14, v16
	v_sub_f32_e32 v13, v13, v16
	v_sub_f32_e32 v12, v12, v16
	v_pk_mul_f32 v[12:13], v[16:17], v[12:13] op_sel:[1,0]
	v_pk_mul_f32 v[14:15], v[16:17], v[14:15] op_sel:[1,0]
	v_pk_fma_f32 v[12:13], v[210:211], v[12:13], v[226:227]
	v_pk_fma_f32 v[14:15], v[212:213], v[14:15], v[228:229]
	v_lshl_add_u64 v[18:19], v[26:27], 2, s[96:97]
	v_lshl_add_u64 v[20:21], v[26:27], 1, s[6:7]
	global_store_dwordx4 v[18:19], v[12:15], off
	s_cbranch_vccnz .LBB0_565
	s_nop 0
	v_cvt_pk_bf16_f32 v12, v12, v13
	v_cvt_pk_bf16_f32 v13, v14, v15
	global_store_dwordx2 v[20:21], v[12:13], off
.LBB0_565:
	s_nop 0
	v_mov_b32_e32 v12, v17
	v_mov_b32_e32 v13, v17
	v_sub_f32_e32 v11, v11, v16
	v_sub_f32_e32 v10, v10, v16
	v_sub_f32_e32 v9, v9, v16
	v_sub_f32_e32 v8, v8, v16
	v_mov_b32_e32 v14, v17
	v_mov_b32_e32 v15, v17
	v_pk_mul_f32 v[8:9], v[12:13], v[8:9]
	v_pk_mul_f32 v[10:11], v[14:15], v[10:11]
	s_and_b64 vcc, exec, s[38:39]
	v_pk_fma_f32 v[10:11], v[10:11], v[216:217], v[232:233]
	v_pk_fma_f32 v[8:9], v[8:9], v[214:215], v[230:231]
	global_store_dwordx4 v[18:19], v[8:11], off offset:64
	s_cbranch_vccnz .LBB0_567
	s_nop 0
	v_cvt_pk_bf16_f32 v8, v8, v9
	v_cvt_pk_bf16_f32 v9, v10, v11
	global_store_dwordx2 v[20:21], v[8:9], off offset:32
.LBB0_567:
	s_nop 0
	v_sub_f32_e32 v7, v7, v16
	v_sub_f32_e32 v6, v6, v16
	v_sub_f32_e32 v5, v5, v16
	v_sub_f32_e32 v4, v4, v16
	v_pk_mul_f32 v[4:5], v[12:13], v[4:5]
	v_pk_mul_f32 v[6:7], v[14:15], v[6:7]
	s_and_b64 vcc, exec, s[38:39]
	v_pk_fma_f32 v[6:7], v[6:7], v[220:221], v[236:237]
	v_pk_fma_f32 v[4:5], v[4:5], v[218:219], v[234:235]
	global_store_dwordx4 v[18:19], v[4:7], off offset:512
	s_cbranch_vccnz .LBB0_569
	s_nop 0
	v_cvt_pk_bf16_f32 v4, v4, v5
	v_cvt_pk_bf16_f32 v5, v6, v7
	global_store_dwordx2 v[20:21], v[4:5], off offset:256
.LBB0_569:
	s_nop 0
	v_sub_f32_e32 v3, v3, v16
	v_sub_f32_e32 v2, v2, v16
	v_sub_f32_e32 v1, v1, v16
	v_sub_f32_e32 v0, v0, v16
	v_mov_b32_e32 v16, v17
	v_pk_mul_f32 v[0:1], v[12:13], v[0:1]
	v_pk_mul_f32 v[2:3], v[16:17], v[2:3]
	s_and_b64 vcc, exec, s[38:39]
	v_pk_fma_f32 v[2:3], v[2:3], v[224:225], v[240:241]
	v_pk_fma_f32 v[0:1], v[0:1], v[222:223], v[238:239]
	global_store_dwordx4 v[18:19], v[0:3], off offset:576
	s_cbranch_vccnz .LBB0_571
	s_nop 0
	v_cvt_pk_bf16_f32 v0, v0, v1
	v_cvt_pk_bf16_f32 v1, v2, v3
	global_store_dwordx2 v[20:21], v[0:1], off offset:288
